# head-rms/final-norm/gate 32-lane sums use DPP adds for 4 of 5 butterfly stages instead of LDS swizzle round trips; meta-row mini GEMM K loop prefetches the next K chunk into a second register bank
# speedup vs baseline: 1.0105x; 1.0105x over previous
; DI unsigned cvt_pk_bf16(float lo, float hi) { const f32x2_t v = {lo, hi}; const bf16v2_t b = __builtin_convertvector(v, bf16v2_t); return __builtin_bit_cast(unsigned, b); }
; #define MFMA16(a, b, c) __builtin_amdgcn_mfma_f32_16x16x32_bf16((a), (b), (c), 0, 0, 0)
;     DI void operator()(int row, int col, f32x4 a) const {
;         bf16_t* d = o + (size_t)row * 2048 + col;
;         const u32x2 ov = *(const u32x2*)d;
;         float of[4] = {__uint_as_float(ov.x << 16), __uint_as_float(ov.x & 0xffff0000u), __uint_as_float(ov.y << 16), __uint_as_float(ov.y & 0xffff0000u)};
;         float y[4];
; #pragma unroll
;         for (int i = 0; i < 4; ++i) { const float z = a[i]; y[i] = z * __builtin_amdgcn_rcpf(1.f + __expf(-z)) * of[i]; }
;         u32x2 w; w.x = cvt_pk_bf16(y[0], y[1]); w.y = cvt_pk_bf16(y[2], y[3]); if (!dry) *(u32x2*)d = w;
; template <class St>
; DI void mini_gemm(int wid0, const bf16_t* A, int lda, int arow0, int nrt, const bf16_t* Bt, int K, int N, const St& st) {
;     ...
;     for (int t = gw; t < nrt * nct; t += nw) {
;         const int rt = t % nrt, ct = t / nrt;
;         const bf16_t* ap = A + (size_t)(arow0 + rt * 16 + (lane & 15)) * lda + 8 * (lane >> 4);
;         const bf16_t* bp = Bt + (size_t)(ct * 16 + (lane & 15)) * K + 8 * (lane >> 4);
;         f32x4 acc0 = (f32x4){0.f, 0.f, 0.f, 0.f}, acc1 = (f32x4){0.f, 0.f, 0.f, 0.f};
;         for (int k0 = 0; k0 < K; k0 += 256) {
;             bf16x8 a[8], b[8];
; #pragma unroll
;             for (int j = 0; j < 8; ++j) { a[j] = *(const bf16x8*)(ap + k0 + 32 * j); b[j] = *(const bf16x8*)(bp + k0 + 32 * j); }
; #pragma unroll
;             for (int j = 0; j < 8; j += 2) { acc0 = MFMA16(b[j], a[j], acc0); acc1 = MFMA16(b[j + 1], a[j + 1], acc1); }
;         }
;         st(arow0 + rt * 16 + (lane & 15), ct * 16 + 4 * (lane >> 4), acc0 + acc1);
.LBB0_67:
	v_add_u32_e32 v8, v17, v0
	v_ashrrev_i32_e32 v9, 31, v8
	v_lshlrev_b64 v[8:9], 11, v[8:9]
	v_lshl_add_u64 v[8:9], v[4:5], 0, v[8:9]
	global_load_dwordx4 v[10:13], v[2:3], off
	global_load_dwordx4 v[20:23], v[8:9], off
	global_load_dwordx4 v[24:27], v[2:3], off offset:64
	global_load_dwordx4 v[28:31], v[8:9], off offset:64
	global_load_dwordx4 v[32:35], v[2:3], off offset:128
	global_load_dwordx4 v[36:39], v[8:9], off offset:128
	global_load_dwordx4 v[40:43], v[2:3], off offset:192
	global_load_dwordx4 v[44:47], v[8:9], off offset:192
	global_load_dwordx4 v[48:51], v[2:3], off offset:256
	global_load_dwordx4 v[52:55], v[8:9], off offset:256
	global_load_dwordx4 v[56:59], v[2:3], off offset:320
	global_load_dwordx4 v[60:63], v[8:9], off offset:320
	global_load_dwordx4 v[64:67], v[2:3], off offset:384
	global_load_dwordx4 v[68:71], v[8:9], off offset:384
	global_load_dwordx4 v[72:75], v[2:3], off offset:448
	global_load_dwordx4 v[76:79], v[8:9], off offset:448
	v_add_u32_e32 v16, s2, v16
	v_cmp_lt_i32_e32 vcc, s38, v16
	s_or_b64 s[6:7], vcc, s[6:7]
	global_load_dwordx4 v[88:91], v[2:3], off offset:512
	global_load_dwordx4 v[92:95], v[8:9], off offset:512
	global_load_dwordx4 v[96:99], v[2:3], off offset:576
	global_load_dwordx4 v[100:103], v[8:9], off offset:576
	global_load_dwordx4 v[104:107], v[2:3], off offset:640
	global_load_dwordx4 v[108:111], v[8:9], off offset:640
	global_load_dwordx4 v[112:115], v[2:3], off offset:704
	global_load_dwordx4 v[116:119], v[8:9], off offset:704
	global_load_dwordx4 v[120:123], v[2:3], off offset:768
	global_load_dwordx4 v[124:127], v[8:9], off offset:768
	global_load_dwordx4 v[128:131], v[2:3], off offset:832
	global_load_dwordx4 v[132:135], v[8:9], off offset:832
	global_load_dwordx4 v[136:139], v[2:3], off offset:896
	global_load_dwordx4 v[140:143], v[8:9], off offset:896
	global_load_dwordx4 v[144:147], v[2:3], off offset:960
	global_load_dwordx4 v[148:151], v[8:9], off offset:960
	s_waitcnt vmcnt(30)
	v_mfma_f32_16x16x32_bf16 v[10:13], v[20:23], v[10:13], 0
	s_waitcnt vmcnt(28)
	v_mfma_f32_16x16x32_bf16 v[20:23], v[28:31], v[24:27], 0
	s_waitcnt vmcnt(26)
	v_mfma_f32_16x16x32_bf16 v[10:13], v[36:39], v[32:35], v[10:13]
	s_waitcnt vmcnt(24)
	v_mfma_f32_16x16x32_bf16 v[20:23], v[44:47], v[40:43], v[20:23]
	s_waitcnt vmcnt(22)
	v_mfma_f32_16x16x32_bf16 v[10:13], v[52:55], v[48:51], v[10:13]
	s_waitcnt vmcnt(20)
	v_mfma_f32_16x16x32_bf16 v[20:23], v[60:63], v[56:59], v[20:23]
	s_waitcnt vmcnt(18)
	v_mfma_f32_16x16x32_bf16 v[10:13], v[68:71], v[64:67], v[10:13]
	s_waitcnt vmcnt(16)
	v_mfma_f32_16x16x32_bf16 v[20:23], v[76:79], v[72:75], v[20:23]
	global_load_dwordx4 v[24:27], v[2:3], off offset:1024
	global_load_dwordx4 v[28:31], v[8:9], off offset:1024
	global_load_dwordx4 v[32:35], v[2:3], off offset:1088
	global_load_dwordx4 v[36:39], v[8:9], off offset:1088
	global_load_dwordx4 v[40:43], v[2:3], off offset:1152
	global_load_dwordx4 v[44:47], v[8:9], off offset:1152
	global_load_dwordx4 v[48:51], v[2:3], off offset:1216
	global_load_dwordx4 v[52:55], v[8:9], off offset:1216
	global_load_dwordx4 v[56:59], v[2:3], off offset:1280
	global_load_dwordx4 v[60:63], v[8:9], off offset:1280
	global_load_dwordx4 v[64:67], v[2:3], off offset:1344
	global_load_dwordx4 v[68:71], v[8:9], off offset:1344
	global_load_dwordx4 v[72:75], v[2:3], off offset:1408
	global_load_dwordx4 v[76:79], v[8:9], off offset:1408
	global_load_dwordx4 v[80:83], v[2:3], off offset:1472
	global_load_dwordx4 v[84:87], v[8:9], off offset:1472
	s_waitcnt vmcnt(30)
	v_mfma_f32_16x16x32_bf16 v[10:13], v[92:95], v[88:91], v[10:13]
	s_waitcnt vmcnt(28)
	v_mfma_f32_16x16x32_bf16 v[20:23], v[100:103], v[96:99], v[20:23]
	s_waitcnt vmcnt(26)
	v_mfma_f32_16x16x32_bf16 v[10:13], v[108:111], v[104:107], v[10:13]
	s_waitcnt vmcnt(24)
	v_mfma_f32_16x16x32_bf16 v[20:23], v[116:119], v[112:115], v[20:23]
	s_waitcnt vmcnt(22)
; DI unsigned cvt_pk_bf16(float lo, float hi) { const f32x2_t v = {lo, hi}; const bf16v2_t b = __builtin_convertvector(v, bf16v2_t); return __builtin_bit_cast(unsigned, b); }
; #define MFMA16(a, b, c) __builtin_amdgcn_mfma_f32_16x16x32_bf16((a), (b), (c), 0, 0, 0)
;     DI void operator()(int row, int col, f32x4 a) const {
;         bf16_t* d = o + (size_t)row * 2048 + col;
;         const u32x2 ov = *(const u32x2*)d;
;         float of[4] = {__uint_as_float(ov.x << 16), __uint_as_float(ov.x & 0xffff0000u), __uint_as_float(ov.y << 16), __uint_as_float(ov.y & 0xffff0000u)};
;         float y[4];
; #pragma unroll
;         for (int i = 0; i < 4; ++i) { const float z = a[i]; y[i] = z * __builtin_amdgcn_rcpf(1.f + __expf(-z)) * of[i]; }
;         u32x2 w; w.x = cvt_pk_bf16(y[0], y[1]); w.y = cvt_pk_bf16(y[2], y[3]); if (!dry) *(u32x2*)d = w;
; template <class St>
; DI void mini_gemm(int wid0, const bf16_t* A, int lda, int arow0, int nrt, const bf16_t* Bt, int K, int N, const St& st) {
;     ...
;     for (int t = gw; t < nrt * nct; t += nw) {
;         const int rt = t % nrt, ct = t / nrt;
;         const bf16_t* ap = A + (size_t)(arow0 + rt * 16 + (lane & 15)) * lda + 8 * (lane >> 4);
;         const bf16_t* bp = Bt + (size_t)(ct * 16 + (lane & 15)) * K + 8 * (lane >> 4);
;         f32x4 acc0 = (f32x4){0.f, 0.f, 0.f, 0.f}, acc1 = (f32x4){0.f, 0.f, 0.f, 0.f};
;         for (int k0 = 0; k0 < K; k0 += 256) {
;             bf16x8 a[8], b[8];
; #pragma unroll
;             for (int j = 0; j < 8; ++j) { a[j] = *(const bf16x8*)(ap + k0 + 32 * j); b[j] = *(const bf16x8*)(bp + k0 + 32 * j); }
; #pragma unroll
;             for (int j = 0; j < 8; j += 2) { acc0 = MFMA16(b[j], a[j], acc0); acc1 = MFMA16(b[j + 1], a[j + 1], acc1); }
;         }
;         st(arow0 + rt * 16 + (lane & 15), ct * 16 + 4 * (lane >> 4), acc0 + acc1);
	v_mfma_f32_16x16x32_bf16 v[10:13], v[124:127], v[120:123], v[10:13]
	s_waitcnt vmcnt(20)
	v_mfma_f32_16x16x32_bf16 v[20:23], v[132:135], v[128:131], v[20:23]
	s_waitcnt vmcnt(18)
	v_mfma_f32_16x16x32_bf16 v[10:13], v[140:143], v[136:139], v[10:13]
	s_waitcnt vmcnt(16)
	v_mfma_f32_16x16x32_bf16 v[20:23], v[148:151], v[144:147], v[20:23]
	global_load_dwordx4 v[88:91], v[2:3], off offset:1536
	global_load_dwordx4 v[92:95], v[8:9], off offset:1536
	global_load_dwordx4 v[96:99], v[2:3], off offset:1600
	global_load_dwordx4 v[100:103], v[8:9], off offset:1600
	global_load_dwordx4 v[104:107], v[2:3], off offset:1664
	global_load_dwordx4 v[108:111], v[8:9], off offset:1664
	global_load_dwordx4 v[112:115], v[2:3], off offset:1728
	global_load_dwordx4 v[116:119], v[8:9], off offset:1728
	global_load_dwordx4 v[120:123], v[2:3], off offset:1792
	global_load_dwordx4 v[124:127], v[8:9], off offset:1792
	global_load_dwordx4 v[128:131], v[2:3], off offset:1856
	global_load_dwordx4 v[132:135], v[8:9], off offset:1856
	global_load_dwordx4 v[136:139], v[2:3], off offset:1920
	global_load_dwordx4 v[140:143], v[8:9], off offset:1920
	global_load_dwordx4 v[144:147], v[2:3], off offset:1984
	global_load_dwordx4 v[148:151], v[8:9], off offset:1984
	s_waitcnt vmcnt(30)
	v_mfma_f32_16x16x32_bf16 v[10:13], v[28:31], v[24:27], v[10:13]
	s_waitcnt vmcnt(28)
	v_mfma_f32_16x16x32_bf16 v[20:23], v[36:39], v[32:35], v[20:23]
	s_waitcnt vmcnt(26)
	v_mfma_f32_16x16x32_bf16 v[10:13], v[44:47], v[40:43], v[10:13]
	s_waitcnt vmcnt(24)
	v_mfma_f32_16x16x32_bf16 v[20:23], v[52:55], v[48:51], v[20:23]
	s_waitcnt vmcnt(22)
	v_mfma_f32_16x16x32_bf16 v[10:13], v[60:63], v[56:59], v[10:13]
	s_waitcnt vmcnt(20)
	v_mfma_f32_16x16x32_bf16 v[20:23], v[68:71], v[64:67], v[20:23]
	s_waitcnt vmcnt(18)
	v_mfma_f32_16x16x32_bf16 v[10:13], v[76:79], v[72:75], v[10:13]
	s_waitcnt vmcnt(16)
	v_mfma_f32_16x16x32_bf16 v[20:23], v[84:87], v[80:83], v[20:23]
	s_waitcnt vmcnt(14)
	v_mfma_f32_16x16x32_bf16 v[8:11], v[92:95], v[88:91], v[10:13]
	s_waitcnt vmcnt(12)
	v_mfma_f32_16x16x32_bf16 v[12:15], v[100:103], v[96:99], v[20:23]
	s_waitcnt vmcnt(10)
	v_mfma_f32_16x16x32_bf16 v[8:11], v[108:111], v[104:107], v[8:11]
	s_waitcnt vmcnt(8)
	v_mfma_f32_16x16x32_bf16 v[12:15], v[116:119], v[112:115], v[12:15]
	s_waitcnt vmcnt(6)
	v_mfma_f32_16x16x32_bf16 v[8:11], v[124:127], v[120:123], v[8:11]
	s_waitcnt vmcnt(4)
	v_mfma_f32_16x16x32_bf16 v[12:15], v[132:135], v[128:131], v[12:15]
	s_waitcnt vmcnt(2)
	v_mfma_f32_16x16x32_bf16 v[20:23], v[140:143], v[136:139], v[8:11]
	s_waitcnt vmcnt(0)
	v_mfma_f32_16x16x32_bf16 v[10:13], v[148:151], v[144:147], v[12:15]
	s_nop 3
	v_add_u32_e32 v14, v18, v0
	v_ashrrev_i32_e32 v15, 31, v14
	v_lshl_add_u64 v[14:15], v[14:15], 1, v[6:7]
	s_nop 0
	v_pk_add_f32 v[10:11], v[20:21], v[10:11]
	global_load_dwordx2 v[20:21], v[14:15], off
	v_pk_add_f32 v[8:9], v[22:23], v[12:13]
	v_mul_f32_e32 v12, 0xbfb8aa3b, v10
	v_mul_f32_e32 v13, 0xbfb8aa3b, v11
	v_exp_f32_e32 v12, v12
	v_exp_f32_e32 v13, v13
	v_add_u32_e32 v0, s10, v0
	v_add_f32_e32 v12, 1.0, v12
	v_add_f32_e32 v13, 1.0, v13
	v_rcp_f32_e32 v12, v12
	v_rcp_f32_e32 v13, v13
	s_nop 0
	v_pk_mul_f32 v[10:11], v[10:11], v[12:13]
	s_waitcnt vmcnt(0)
	v_lshlrev_b32_e32 v12, 16, v20
	v_and_b32_e32 v13, 0xffff0000, v20
	v_pk_mul_f32 v[10:11], v[10:11], v[12:13]
	v_mul_f32_e32 v12, 0xbfb8aa3b, v8
	v_mul_f32_e32 v13, 0xbfb8aa3b, v9
	v_exp_f32_e32 v12, v12
	v_exp_f32_e32 v13, v13
	v_cvt_pk_bf16_f32 v10, v10, v11
	v_add_f32_e32 v12, 1.0, v12
	v_add_f32_e32 v13, 1.0, v13
	v_rcp_f32_e32 v12, v12
	v_rcp_f32_e32 v13, v13
	s_nop 0
	v_pk_mul_f32 v[8:9], v[8:9], v[12:13]
	v_lshlrev_b32_e32 v12, 16, v21
	v_and_b32_e32 v13, 0xffff0000, v21
	v_pk_mul_f32 v[8:9], v[8:9], v[12:13]
	s_nop 0
	v_cvt_pk_bf16_f32 v11, v8, v9
	global_store_dwordx2 v[14:15], v[10:11], off
	s_andn2_b64 exec, exec, s[6:7]
	s_cbranch_execnz .LBB0_67

; DI unsigned cvt_pk_bf16(float lo, float hi) { const f32x2_t v = {lo, hi}; const bf16v2_t b = __builtin_convertvector(v, bf16v2_t); return __builtin_bit_cast(unsigned, b); }
; #define SWZ_XOR(v, x) __int_as_float(__builtin_amdgcn_ds_swizzle(__float_as_int(v), 0x1F | ((x) << 10)))
; DI float half_sum(float v) { v += SWZ_XOR(v, 1); v += SWZ_XOR(v, 2); v += SWZ_XOR(v, 4); v += SWZ_XOR(v, 8); v += SWZ_XOR(v, 16); return v; }
; DI void finalize_attn(const Params& p, unsigned char* lds, f32x16 (&o)[8], float l_reg, int lane_k, int wid, bool meta, int qrow0, int hh, int di, float lambda_init, bool dry) {
;     ...
;         for (int it = 0; it < 16; ++it) {
;             const int row = 2 * it + (lane >> 5);
;             f32x4 a = *(const f32x4*)(R + row * 256 + c8), b = *(const f32x4*)(R + row * 256 + c8 + 4);
;             float ss = a[0] * a[0] + a[1] * a[1] + a[2] * a[2] + a[3] * a[3] + b[0] * b[0] + b[1] * b[1] + b[2] * b[2] + b[3] * b[3];
;             ss = half_sum(ss);
;             const float rstd = rsqrtf(ss * (1.f / 256.f) + 1e-6f);
;             a = a * rstd * g0; b = b * rstd * g1;
;             u32x4 w; w.x = cvt_pk_bf16(a[0], a[1]); w.y = cvt_pk_bf16(a[2], a[3]); w.z = cvt_pk_bf16(b[0], b[1]); w.w = cvt_pk_bf16(b[2], b[3]);
;             if (row < nrow) *(u32x4*)(dstb + (size_t)it * 4096) = w;
;         }
.LBB0_124:
	ds_read_b128 v[6:9], v20
	ds_read_b128 v[2:5], v20 offset:16
	v_add_u32_e32 v21, s7, v0
	v_cmp_gt_i32_e32 vcc, s6, v21
	s_waitcnt lgkmcnt(1)
	v_mul_f32_e32 v22, v7, v7
	v_fmac_f32_e32 v22, v6, v6
	v_fmac_f32_e32 v22, v8, v8
	v_fmac_f32_e32 v22, v9, v9
	s_waitcnt lgkmcnt(0)
	v_fmac_f32_e32 v22, v2, v2
	v_fmac_f32_e32 v22, v3, v3
	v_fmac_f32_e32 v22, v4, v4
	v_fmac_f32_e32 v22, v5, v5
	s_nop 1
	v_add_f32_dpp v22, v22, v22 quad_perm:[1,0,3,2] row_mask:0xf bank_mask:0xf
	s_nop 1
	v_add_f32_dpp v22, v22, v22 quad_perm:[2,3,0,1] row_mask:0xf bank_mask:0xf
	s_nop 1
	v_add_f32_dpp v22, v22, v22 row_half_mirror row_mask:0xf bank_mask:0xf
	s_nop 1
	v_add_f32_dpp v22, v22, v22 row_mirror row_mask:0xf bank_mask:0xf
	ds_swizzle_b32 v23, v22 offset:swizzle(SWAP,16)
	s_and_saveexec_b64 s[8:9], vcc
	s_cbranch_execz .LBB0_126
	s_waitcnt lgkmcnt(0)
	v_add_f32_e32 v22, v22, v23
	v_fmamk_f32 v22, v22, 0x3b800000, v185
	v_mul_f32_e32 v23, 0x4b800000, v22
	v_cmp_gt_f32_e32 vcc, s25, v22
	s_nop 1
	v_cndmask_b32_e32 v22, v22, v23, vcc
	v_rsq_f32_e32 v22, v22
	s_nop 0
	v_mul_f32_e32 v23, 0x45800000, v22
	v_cndmask_b32_e32 v22, v22, v23, vcc
	v_pk_mul_f32 v[6:7], v[6:7], v[22:23] op_sel_hi:[1,0]
	v_pk_mul_f32 v[8:9], v[8:9], v[22:23] op_sel_hi:[1,0]
	v_pk_mul_f32 v[2:3], v[2:3], v[22:23] op_sel_hi:[1,0]
	v_pk_mul_f32 v[8:9], v[10:11], v[8:9]
	v_pk_mul_f32 v[6:7], v[12:13], v[6:7]
	v_pk_mul_f32 v[4:5], v[4:5], v[22:23] op_sel_hi:[1,0]
	v_pk_mul_f32 v[2:3], v[16:17], v[2:3]
	v_cvt_pk_bf16_f32 v6, v6, v7
	v_cvt_pk_bf16_f32 v7, v8, v9
	v_pk_mul_f32 v[4:5], v[14:15], v[4:5]
	v_cvt_pk_bf16_f32 v8, v2, v3
	v_add_co_u32_e32 v2, vcc, 0xffffe000, v18
	v_cvt_pk_bf16_f32 v9, v4, v5
	s_nop 0
	v_addc_co_u32_e32 v3, vcc, -1, v19, vcc
	global_store_dwordx4 v[2:3], v[6:9], off
.LBB0_126:
	s_or_b64 exec, exec, s[8:9]
	ds_read_b128 v[6:9], v20 offset:2048
	ds_read_b128 v[2:5], v20 offset:2064
	v_add_u32_e32 v21, 2, v21
	v_cmp_gt_i32_e32 vcc, s6, v21
	s_waitcnt lgkmcnt(1)
	v_mul_f32_e32 v22, v7, v7
	v_fmac_f32_e32 v22, v6, v6
	v_fmac_f32_e32 v22, v8, v8
	v_fmac_f32_e32 v22, v9, v9
	s_waitcnt lgkmcnt(0)
	v_fmac_f32_e32 v22, v2, v2
	v_fmac_f32_e32 v22, v3, v3
	v_fmac_f32_e32 v22, v4, v4
	v_fmac_f32_e32 v22, v5, v5
	s_nop 1
	v_add_f32_dpp v22, v22, v22 quad_perm:[1,0,3,2] row_mask:0xf bank_mask:0xf
	s_nop 1
	v_add_f32_dpp v22, v22, v22 quad_perm:[2,3,0,1] row_mask:0xf bank_mask:0xf
	s_nop 1
	v_add_f32_dpp v22, v22, v22 row_half_mirror row_mask:0xf bank_mask:0xf
	s_nop 1
	v_add_f32_dpp v22, v22, v22 row_mirror row_mask:0xf bank_mask:0xf
	ds_swizzle_b32 v23, v22 offset:swizzle(SWAP,16)
	s_and_saveexec_b64 s[8:9], vcc
	s_cbranch_execz .LBB0_123
	s_waitcnt lgkmcnt(0)
	v_add_f32_e32 v21, v22, v23
	v_fmamk_f32 v21, v21, 0x3b800000, v185
	v_mul_f32_e32 v22, 0x4b800000, v21
	v_cmp_gt_f32_e32 vcc, s25, v21
	s_nop 1
	v_cndmask_b32_e32 v21, v21, v22, vcc
	v_rsq_f32_e32 v21, v21
	s_nop 0
	v_mul_f32_e32 v22, 0x45800000, v21
	v_cndmask_b32_e32 v22, v21, v22, vcc
	v_pk_mul_f32 v[6:7], v[6:7], v[22:23] op_sel_hi:[1,0]
	v_pk_mul_f32 v[8:9], v[8:9], v[22:23] op_sel_hi:[1,0]
	v_pk_mul_f32 v[2:3], v[2:3], v[22:23] op_sel_hi:[1,0]
	v_pk_mul_f32 v[4:5], v[4:5], v[22:23] op_sel_hi:[1,0]
	v_pk_mul_f32 v[8:9], v[10:11], v[8:9]
	v_pk_mul_f32 v[6:7], v[12:13], v[6:7]
	v_pk_mul_f32 v[4:5], v[14:15], v[4:5]
	v_pk_mul_f32 v[2:3], v[16:17], v[2:3]
	v_cvt_pk_bf16_f32 v6, v6, v7
	v_cvt_pk_bf16_f32 v7, v8, v9
	v_cvt_pk_bf16_f32 v8, v2, v3
	v_cvt_pk_bf16_f32 v9, v4, v5
	global_store_dwordx4 v[18:19], v[6:9], off
	s_branch .LBB0_123

; DI int opaque_bid() { int b = blockIdx.x; asm volatile("" : "+s"(b)); return b; }
; DI int opaque_gdim() { int g = gridDim.x; asm volatile("" : "+s"(g)); return g; }
; #define SWZ_XOR(v, x) __int_as_float(__builtin_amdgcn_ds_swizzle(__float_as_int(v), 0x1F | ((x) << 10)))
; DI float half_sum(float v) { v += SWZ_XOR(v, 1); v += SWZ_XOR(v, 2); v += SWZ_XOR(v, 4); v += SWZ_XOR(v, 8); v += SWZ_XOR(v, 16); return v; }
; DI float wave_sum(float v) { v = half_sum(v); auto rr = __builtin_amdgcn_permlane32_swap(__float_as_uint(v), __float_as_uint(v), false, false); return __uint_as_float(rr[0]) + __uint_as_float(rr[1]); }
; DI void phase_final(int wid0, const Params& p) {
;     ...
;     for (int row = opaque_bid() * 8 + wave; row < MREG; row += opaque_gdim() * 8) {
;         float* src = p.out + (size_t)row * 1024;
;         f32x4 v[4]; float ss = 0.f;
; #pragma unroll
;         for (int i = 0; i < 4; ++i) { v[i] = *(const f32x4*)(src + i * 256 + lane * 4); ss += v[i][0] * v[i][0] + v[i][1] * v[i][1] + v[i][2] * v[i][2] + v[i][3] * v[i][3]; }
;         ss = wave_sum(ss);
;         const float rstd = rsqrtf(ss * (1.f / 1024.f) + 1e-6f);
; #pragma unroll
;         for (int i = 0; i < 4; ++i) { const f32x4 gv = *(const f32x4*)(p.g_final + i * 256 + lane * 4); *(f32x4*)(src + i * 256 + lane * 4) = v[i] * rstd * gv; }
;     }
.LBB0_182:
	v_ashrrev_i32_e32 v19, 31, v18
	v_lshlrev_b64 v[2:3], 12, v[18:19]
	v_lshl_add_u64 v[24:25], v[20:21], 0, v[2:3]
	global_load_dwordx4 v[2:5], v[24:25], off
	global_load_dwordx4 v[6:9], v[24:25], off offset:1024
	global_load_dwordx4 v[26:29], v[22:23], off
	s_mov_b32 s2, s20
	s_waitcnt vmcnt(2)
	v_mul_f32_e32 v0, v3, v3
	s_waitcnt vmcnt(1)
	v_mul_f32_e32 v10, v7, v7
	v_fmac_f32_e32 v0, v2, v2
	v_fmac_f32_e32 v10, v6, v6
	v_fmac_f32_e32 v0, v4, v4
	v_fmac_f32_e32 v10, v8, v8
	v_fmac_f32_e32 v0, v5, v5
	v_fmac_f32_e32 v10, v9, v9
	v_add_f32_e32 v0, v0, v10
	global_load_dwordx4 v[10:13], v[24:25], off offset:2048
	s_waitcnt vmcnt(0)
	v_mul_f32_e32 v14, v11, v11
	v_fmac_f32_e32 v14, v10, v10
	v_fmac_f32_e32 v14, v12, v12
	v_fmac_f32_e32 v14, v13, v13
	v_add_f32_e32 v0, v0, v14
	global_load_dwordx4 v[14:17], v[24:25], off offset:3072
	s_waitcnt vmcnt(0)
	v_mul_f32_e32 v19, v15, v15
	v_fmac_f32_e32 v19, v14, v14
	v_fmac_f32_e32 v19, v16, v16
	v_fmac_f32_e32 v19, v17, v17
	v_add_f32_e32 v0, v0, v19
	s_nop 1
	v_add_f32_dpp v0, v0, v0 quad_perm:[1,0,3,2] row_mask:0xf bank_mask:0xf
	s_nop 1
	v_add_f32_dpp v0, v0, v0 quad_perm:[2,3,0,1] row_mask:0xf bank_mask:0xf
	s_nop 1
	v_add_f32_dpp v0, v0, v0 row_half_mirror row_mask:0xf bank_mask:0xf
	s_nop 1
	v_add_f32_dpp v0, v0, v0 row_mirror row_mask:0xf bank_mask:0xf
	ds_swizzle_b32 v19, v0 offset:swizzle(SWAP,16)
	s_waitcnt lgkmcnt(0)
	v_add_f32_e32 v0, v0, v19
	v_mov_b32_e32 v19, v0
	s_nop 1
	v_permlane32_swap_b32_e32 v0, v19
	v_add_f32_e32 v0, v0, v19
	v_fmamk_f32 v0, v0, 0x3a800000, v185
	v_cmp_gt_f32_e32 vcc, s25, v0
	v_mul_f32_e32 v19, 0x4b800000, v0
	s_nop 0
	v_cndmask_b32_e32 v0, v0, v19, vcc
	v_rsq_f32_e32 v0, v0
	s_nop 0
	v_mul_f32_e32 v19, 0x45800000, v0
	v_cndmask_b32_e32 v0, v0, v19, vcc
	v_pk_mul_f32 v[2:3], v[2:3], v[0:1] op_sel_hi:[1,0]
	v_pk_mul_f32 v[4:5], v[4:5], v[0:1] op_sel_hi:[1,0]
	v_pk_mul_f32 v[2:3], v[26:27], v[2:3]
	v_pk_mul_f32 v[4:5], v[28:29], v[4:5]
	global_store_dwordx4 v[24:25], v[2:5], off
	global_load_dwordx4 v[2:5], v[22:23], off offset:1024
	v_pk_mul_f32 v[8:9], v[8:9], v[0:1] op_sel_hi:[1,0]
	v_pk_mul_f32 v[6:7], v[6:7], v[0:1] op_sel_hi:[1,0]
	s_waitcnt vmcnt(0)
	v_pk_mul_f32 v[4:5], v[4:5], v[8:9]
	v_pk_mul_f32 v[2:3], v[2:3], v[6:7]
	global_store_dwordx4 v[24:25], v[2:5], off offset:1024
	global_load_dwordx4 v[2:5], v[22:23], off offset:2048
	v_pk_mul_f32 v[6:7], v[12:13], v[0:1] op_sel_hi:[1,0]
	v_pk_mul_f32 v[8:9], v[10:11], v[0:1] op_sel_hi:[1,0]
	s_waitcnt vmcnt(0)
	v_pk_mul_f32 v[4:5], v[4:5], v[6:7]
	v_pk_mul_f32 v[2:3], v[2:3], v[8:9]
	global_store_dwordx4 v[24:25], v[2:5], off offset:2048
	global_load_dwordx4 v[2:5], v[22:23], off offset:3072
	v_pk_mul_f32 v[6:7], v[16:17], v[0:1] op_sel_hi:[1,0]
	v_pk_mul_f32 v[8:9], v[14:15], v[0:1] op_sel_hi:[1,0]
	s_waitcnt vmcnt(0)
	v_pk_mul_f32 v[4:5], v[4:5], v[6:7]
	v_pk_mul_f32 v[2:3], v[2:3], v[8:9]
	global_store_dwordx4 v[24:25], v[2:5], off offset:3072
	s_nop 0
	v_lshl_add_u32 v18, s2, 3, v18
	v_cmp_lt_i32_e32 vcc, s40, v18
	s_or_b64 s[6:7], vcc, s[6:7]
	s_andn2_b64 exec, exec, s[6:7]
	s_cbranch_execnz .LBB0_182

; #define MFMA16(a, b, c) __builtin_amdgcn_mfma_f32_16x16x32_bf16((a), (b), (c), 0, 0, 0)
; template <class St>
; DI void mini_gemm(int wid0, const bf16_t* A, int lda, int arow0, int nrt, const bf16_t* Bt, int K, int N, const St& st) {
;     ...
;     for (int t = gw; t < nrt * nct; t += nw) {
;         const int rt = t % nrt, ct = t / nrt;
;         const bf16_t* ap = A + (size_t)(arow0 + rt * 16 + (lane & 15)) * lda + 8 * (lane >> 4);
;         const bf16_t* bp = Bt + (size_t)(ct * 16 + (lane & 15)) * K + 8 * (lane >> 4);
;         f32x4 acc0 = (f32x4){0.f, 0.f, 0.f, 0.f}, acc1 = (f32x4){0.f, 0.f, 0.f, 0.f};
;         for (int k0 = 0; k0 < K; k0 += 256) {
;             bf16x8 a[8], b[8];
; #pragma unroll
;             for (int j = 0; j < 8; ++j) { a[j] = *(const bf16x8*)(ap + k0 + 32 * j); b[j] = *(const bf16x8*)(bp + k0 + 32 * j); }
; #pragma unroll
;             for (int j = 0; j < 8; j += 2) { acc0 = MFMA16(b[j], a[j], acc0); acc1 = MFMA16(b[j + 1], a[j + 1], acc1); }
;         }
.LBB0_216:
	v_add_u32_e32 v2, v79, v81
	v_ashrrev_i32_e32 v3, 31, v2
	v_lshlrev_b64 v[2:3], 12, v[2:3]
	v_lshl_add_u64 v[70:71], v[76:77], 0, v[2:3]
	global_load_dwordx4 v[2:5], v[74:75], off
	global_load_dwordx4 v[6:9], v[70:71], off
	global_load_dwordx4 v[10:13], v[74:75], off offset:64
	global_load_dwordx4 v[14:17], v[70:71], off offset:64
	global_load_dwordx4 v[18:21], v[74:75], off offset:128
	global_load_dwordx4 v[22:25], v[70:71], off offset:128
	global_load_dwordx4 v[26:29], v[74:75], off offset:192
	global_load_dwordx4 v[30:33], v[70:71], off offset:192
	global_load_dwordx4 v[34:37], v[74:75], off offset:256
	global_load_dwordx4 v[38:41], v[70:71], off offset:256
	global_load_dwordx4 v[42:45], v[74:75], off offset:320
	global_load_dwordx4 v[46:49], v[70:71], off offset:320
	global_load_dwordx4 v[50:53], v[74:75], off offset:384
	global_load_dwordx4 v[54:57], v[70:71], off offset:384
	global_load_dwordx4 v[58:61], v[74:75], off offset:448
	global_load_dwordx4 v[62:65], v[70:71], off offset:448
	v_add_u32_e32 v78, s2, v78
	v_cmp_lt_i32_e32 vcc, 63, v78
	s_or_b64 s[8:9], vcc, s[8:9]
	global_load_dwordx4 v[86:89], v[74:75], off offset:512
	global_load_dwordx4 v[90:93], v[70:71], off offset:512
	global_load_dwordx4 v[94:97], v[74:75], off offset:576
	global_load_dwordx4 v[98:101], v[70:71], off offset:576
	global_load_dwordx4 v[102:105], v[74:75], off offset:640
	global_load_dwordx4 v[106:109], v[70:71], off offset:640
	global_load_dwordx4 v[110:113], v[74:75], off offset:704
	global_load_dwordx4 v[114:117], v[70:71], off offset:704
	global_load_dwordx4 v[118:121], v[74:75], off offset:768
	global_load_dwordx4 v[122:125], v[70:71], off offset:768
	global_load_dwordx4 v[126:129], v[74:75], off offset:832
	global_load_dwordx4 v[130:133], v[70:71], off offset:832
	global_load_dwordx4 v[134:137], v[74:75], off offset:896
	global_load_dwordx4 v[138:141], v[70:71], off offset:896
	global_load_dwordx4 v[142:145], v[74:75], off offset:960
	global_load_dwordx4 v[158:161], v[70:71], off offset:960
	s_waitcnt vmcnt(30)
	v_mfma_f32_16x16x32_bf16 v[2:5], v[6:9], v[2:5], 0
	s_waitcnt vmcnt(28)
	v_mfma_f32_16x16x32_bf16 v[6:9], v[14:17], v[10:13], 0
	s_waitcnt vmcnt(26)
	v_mfma_f32_16x16x32_bf16 v[2:5], v[22:25], v[18:21], v[2:5]
	s_waitcnt vmcnt(24)
	v_mfma_f32_16x16x32_bf16 v[6:9], v[30:33], v[26:29], v[6:9]
	s_waitcnt vmcnt(22)
	v_mfma_f32_16x16x32_bf16 v[2:5], v[38:41], v[34:37], v[2:5]
	s_waitcnt vmcnt(20)
	v_mfma_f32_16x16x32_bf16 v[6:9], v[46:49], v[42:45], v[6:9]
	s_waitcnt vmcnt(18)
	v_mfma_f32_16x16x32_bf16 v[2:5], v[54:57], v[50:53], v[2:5]
	s_waitcnt vmcnt(16)
	v_mfma_f32_16x16x32_bf16 v[6:9], v[62:65], v[58:61], v[6:9]
	global_load_dwordx4 v[10:13], v[74:75], off offset:1024
	global_load_dwordx4 v[14:17], v[70:71], off offset:1024
	global_load_dwordx4 v[18:21], v[74:75], off offset:1088
	global_load_dwordx4 v[22:25], v[70:71], off offset:1088
	global_load_dwordx4 v[26:29], v[74:75], off offset:1152
	global_load_dwordx4 v[30:33], v[70:71], off offset:1152
	global_load_dwordx4 v[34:37], v[74:75], off offset:1216
	global_load_dwordx4 v[38:41], v[70:71], off offset:1216
	global_load_dwordx4 v[42:45], v[74:75], off offset:1280
	global_load_dwordx4 v[46:49], v[70:71], off offset:1280
	global_load_dwordx4 v[50:53], v[74:75], off offset:1344
	global_load_dwordx4 v[54:57], v[70:71], off offset:1344
	global_load_dwordx4 v[58:61], v[74:75], off offset:1408
	global_load_dwordx4 v[62:65], v[70:71], off offset:1408
	global_load_dwordx4 v[66:69], v[74:75], off offset:1472
	global_load_dwordx4 v[82:85], v[70:71], off offset:1472
	s_waitcnt vmcnt(30)
	v_mfma_f32_16x16x32_bf16 v[2:5], v[90:93], v[86:89], v[2:5]
	s_waitcnt vmcnt(28)
	v_mfma_f32_16x16x32_bf16 v[6:9], v[98:101], v[94:97], v[6:9]
	s_waitcnt vmcnt(26)
	v_mfma_f32_16x16x32_bf16 v[2:5], v[106:109], v[102:105], v[2:5]
	s_waitcnt vmcnt(24)
	v_mfma_f32_16x16x32_bf16 v[6:9], v[114:117], v[110:113], v[6:9]
	s_waitcnt vmcnt(22)
	v_mfma_f32_16x16x32_bf16 v[2:5], v[122:125], v[118:121], v[2:5]
	s_waitcnt vmcnt(20)
	v_mfma_f32_16x16x32_bf16 v[6:9], v[130:133], v[126:129], v[6:9]
	s_waitcnt vmcnt(18)
	v_mfma_f32_16x16x32_bf16 v[2:5], v[138:141], v[134:137], v[2:5]
	s_waitcnt vmcnt(16)
	v_mfma_f32_16x16x32_bf16 v[6:9], v[158:161], v[142:145], v[6:9]
	global_load_dwordx4 v[86:89], v[74:75], off offset:1536
	global_load_dwordx4 v[90:93], v[70:71], off offset:1536
	global_load_dwordx4 v[94:97], v[74:75], off offset:1600
	global_load_dwordx4 v[98:101], v[70:71], off offset:1600
	global_load_dwordx4 v[102:105], v[74:75], off offset:1664
	global_load_dwordx4 v[106:109], v[70:71], off offset:1664
	global_load_dwordx4 v[110:113], v[74:75], off offset:1728
	global_load_dwordx4 v[114:117], v[70:71], off offset:1728
	global_load_dwordx4 v[118:121], v[74:75], off offset:1792
	global_load_dwordx4 v[122:125], v[70:71], off offset:1792
	global_load_dwordx4 v[126:129], v[74:75], off offset:1856
	global_load_dwordx4 v[130:133], v[70:71], off offset:1856
	global_load_dwordx4 v[134:137], v[74:75], off offset:1920
	global_load_dwordx4 v[138:141], v[70:71], off offset:1920
	global_load_dwordx4 v[142:145], v[74:75], off offset:1984
	global_load_dwordx4 v[158:161], v[70:71], off offset:1984
	s_waitcnt vmcnt(30)
	v_mfma_f32_16x16x32_bf16 v[2:5], v[14:17], v[10:13], v[2:5]
	s_waitcnt vmcnt(28)
	v_mfma_f32_16x16x32_bf16 v[6:9], v[22:25], v[18:21], v[6:9]
	s_waitcnt vmcnt(26)
	v_mfma_f32_16x16x32_bf16 v[2:5], v[30:33], v[26:29], v[2:5]
	s_waitcnt vmcnt(24)
	v_mfma_f32_16x16x32_bf16 v[6:9], v[38:41], v[34:37], v[6:9]
	s_waitcnt vmcnt(22)
	v_mfma_f32_16x16x32_bf16 v[2:5], v[46:49], v[42:45], v[2:5]
	s_waitcnt vmcnt(20)
; #define MFMA16(a, b, c) __builtin_amdgcn_mfma_f32_16x16x32_bf16((a), (b), (c), 0, 0, 0)
; template <class St>
; DI void mini_gemm(int wid0, const bf16_t* A, int lda, int arow0, int nrt, const bf16_t* Bt, int K, int N, const St& st) {
;     ...
;     for (int t = gw; t < nrt * nct; t += nw) {
;         const int rt = t % nrt, ct = t / nrt;
;         const bf16_t* ap = A + (size_t)(arow0 + rt * 16 + (lane & 15)) * lda + 8 * (lane >> 4);
;         const bf16_t* bp = Bt + (size_t)(ct * 16 + (lane & 15)) * K + 8 * (lane >> 4);
;         f32x4 acc0 = (f32x4){0.f, 0.f, 0.f, 0.f}, acc1 = (f32x4){0.f, 0.f, 0.f, 0.f};
;         for (int k0 = 0; k0 < K; k0 += 256) {
;             bf16x8 a[8], b[8];
; #pragma unroll
;             for (int j = 0; j < 8; ++j) { a[j] = *(const bf16x8*)(ap + k0 + 32 * j); b[j] = *(const bf16x8*)(bp + k0 + 32 * j); }
; #pragma unroll
;             for (int j = 0; j < 8; j += 2) { acc0 = MFMA16(b[j], a[j], acc0); acc1 = MFMA16(b[j + 1], a[j + 1], acc1); }
;         }
	v_mfma_f32_16x16x32_bf16 v[6:9], v[54:57], v[50:53], v[6:9]
	s_waitcnt vmcnt(18)
	v_mfma_f32_16x16x32_bf16 v[2:5], v[62:65], v[58:61], v[2:5]
	s_waitcnt vmcnt(16)
	v_mfma_f32_16x16x32_bf16 v[6:9], v[82:85], v[66:69], v[6:9]
	global_load_dwordx4 v[10:13], v[74:75], off offset:2048
	global_load_dwordx4 v[14:17], v[70:71], off offset:2048
	global_load_dwordx4 v[18:21], v[74:75], off offset:2112
	global_load_dwordx4 v[22:25], v[70:71], off offset:2112
	global_load_dwordx4 v[26:29], v[74:75], off offset:2176
	global_load_dwordx4 v[30:33], v[70:71], off offset:2176
	global_load_dwordx4 v[34:37], v[74:75], off offset:2240
	global_load_dwordx4 v[38:41], v[70:71], off offset:2240
	global_load_dwordx4 v[42:45], v[74:75], off offset:2304
	global_load_dwordx4 v[46:49], v[70:71], off offset:2304
	global_load_dwordx4 v[50:53], v[74:75], off offset:2368
	global_load_dwordx4 v[54:57], v[70:71], off offset:2368
	global_load_dwordx4 v[58:61], v[74:75], off offset:2432
	global_load_dwordx4 v[62:65], v[70:71], off offset:2432
	global_load_dwordx4 v[66:69], v[74:75], off offset:2496
	global_load_dwordx4 v[82:85], v[70:71], off offset:2496
	s_waitcnt vmcnt(30)
	v_mfma_f32_16x16x32_bf16 v[2:5], v[90:93], v[86:89], v[2:5]
	s_waitcnt vmcnt(28)
	v_mfma_f32_16x16x32_bf16 v[6:9], v[98:101], v[94:97], v[6:9]
	s_waitcnt vmcnt(26)
	v_mfma_f32_16x16x32_bf16 v[2:5], v[106:109], v[102:105], v[2:5]
	s_waitcnt vmcnt(24)
	v_mfma_f32_16x16x32_bf16 v[6:9], v[114:117], v[110:113], v[6:9]
	s_waitcnt vmcnt(22)
	v_mfma_f32_16x16x32_bf16 v[2:5], v[122:125], v[118:121], v[2:5]
	s_waitcnt vmcnt(20)
	v_mfma_f32_16x16x32_bf16 v[6:9], v[130:133], v[126:129], v[6:9]
	s_waitcnt vmcnt(18)
	v_mfma_f32_16x16x32_bf16 v[2:5], v[138:141], v[134:137], v[2:5]
	s_waitcnt vmcnt(16)
	v_mfma_f32_16x16x32_bf16 v[6:9], v[158:161], v[142:145], v[6:9]
	global_load_dwordx4 v[86:89], v[74:75], off offset:2560
	global_load_dwordx4 v[90:93], v[70:71], off offset:2560
	global_load_dwordx4 v[94:97], v[74:75], off offset:2624
	global_load_dwordx4 v[98:101], v[70:71], off offset:2624
	global_load_dwordx4 v[102:105], v[74:75], off offset:2688
	global_load_dwordx4 v[106:109], v[70:71], off offset:2688
	global_load_dwordx4 v[110:113], v[74:75], off offset:2752
	global_load_dwordx4 v[114:117], v[70:71], off offset:2752
	global_load_dwordx4 v[118:121], v[74:75], off offset:2816
	global_load_dwordx4 v[122:125], v[70:71], off offset:2816
	global_load_dwordx4 v[126:129], v[74:75], off offset:2880
	global_load_dwordx4 v[130:133], v[70:71], off offset:2880
	global_load_dwordx4 v[134:137], v[74:75], off offset:2944
	global_load_dwordx4 v[138:141], v[70:71], off offset:2944
	global_load_dwordx4 v[142:145], v[74:75], off offset:3008
	global_load_dwordx4 v[158:161], v[70:71], off offset:3008
	s_waitcnt vmcnt(30)
	v_mfma_f32_16x16x32_bf16 v[2:5], v[14:17], v[10:13], v[2:5]
	s_waitcnt vmcnt(28)
	v_mfma_f32_16x16x32_bf16 v[6:9], v[22:25], v[18:21], v[6:9]
	s_waitcnt vmcnt(26)
	v_mfma_f32_16x16x32_bf16 v[2:5], v[30:33], v[26:29], v[2:5]
	s_waitcnt vmcnt(24)
	v_mfma_f32_16x16x32_bf16 v[6:9], v[38:41], v[34:37], v[6:9]
	s_waitcnt vmcnt(22)
	v_mfma_f32_16x16x32_bf16 v[2:5], v[46:49], v[42:45], v[2:5]
	s_waitcnt vmcnt(20)
	v_mfma_f32_16x16x32_bf16 v[6:9], v[54:57], v[50:53], v[6:9]
	s_waitcnt vmcnt(18)
	v_mfma_f32_16x16x32_bf16 v[2:5], v[62:65], v[58:61], v[2:5]
	s_waitcnt vmcnt(16)
	v_mfma_f32_16x16x32_bf16 v[6:9], v[82:85], v[66:69], v[6:9]
	global_load_dwordx4 v[10:13], v[74:75], off offset:3072
	global_load_dwordx4 v[14:17], v[70:71], off offset:3072
	global_load_dwordx4 v[18:21], v[74:75], off offset:3136
	global_load_dwordx4 v[22:25], v[70:71], off offset:3136
	global_load_dwordx4 v[26:29], v[74:75], off offset:3200
	global_load_dwordx4 v[30:33], v[70:71], off offset:3200
	global_load_dwordx4 v[34:37], v[74:75], off offset:3264
	global_load_dwordx4 v[38:41], v[70:71], off offset:3264
	global_load_dwordx4 v[42:45], v[74:75], off offset:3328
	global_load_dwordx4 v[46:49], v[70:71], off offset:3328
	global_load_dwordx4 v[50:53], v[74:75], off offset:3392
	global_load_dwordx4 v[54:57], v[70:71], off offset:3392
	global_load_dwordx4 v[58:61], v[74:75], off offset:3456
	global_load_dwordx4 v[62:65], v[70:71], off offset:3456
	global_load_dwordx4 v[66:69], v[74:75], off offset:3520
	global_load_dwordx4 v[82:85], v[70:71], off offset:3520
	s_waitcnt vmcnt(30)
; #define MFMA16(a, b, c) __builtin_amdgcn_mfma_f32_16x16x32_bf16((a), (b), (c), 0, 0, 0)
;     DI void operator()(int row, int col, f32x4 a) const {
;         const size_t o = (size_t)(row - rowoff) * 1024 + col;
;         const f32x4 s = *(const f32x4*)(src + o); if (!dry) *(f32x4*)(dst + o) = s + a;
;     }
; template <class St>
; DI void mini_gemm(int wid0, const bf16_t* A, int lda, int arow0, int nrt, const bf16_t* Bt, int K, int N, const St& st) {
;     ...
;         for (int k0 = 0; k0 < K; k0 += 256) {
;             bf16x8 a[8], b[8];
; #pragma unroll
;             for (int j = 0; j < 8; ++j) { a[j] = *(const bf16x8*)(ap + k0 + 32 * j); b[j] = *(const bf16x8*)(bp + k0 + 32 * j); }
; #pragma unroll
;             for (int j = 0; j < 8; j += 2) { acc0 = MFMA16(b[j], a[j], acc0); acc1 = MFMA16(b[j + 1], a[j + 1], acc1); }
;         }
;         st(arow0 + rt * 16 + (lane & 15), ct * 16 + 4 * (lane >> 4), acc0 + acc1);
	v_mfma_f32_16x16x32_bf16 v[2:5], v[90:93], v[86:89], v[2:5]
	s_waitcnt vmcnt(28)
	v_mfma_f32_16x16x32_bf16 v[6:9], v[98:101], v[94:97], v[6:9]
	s_waitcnt vmcnt(26)
	v_mfma_f32_16x16x32_bf16 v[2:5], v[106:109], v[102:105], v[2:5]
	s_waitcnt vmcnt(24)
	v_mfma_f32_16x16x32_bf16 v[6:9], v[114:117], v[110:113], v[6:9]
	s_waitcnt vmcnt(22)
	v_mfma_f32_16x16x32_bf16 v[2:5], v[122:125], v[118:121], v[2:5]
	s_waitcnt vmcnt(20)
	v_mfma_f32_16x16x32_bf16 v[6:9], v[130:133], v[126:129], v[6:9]
	s_waitcnt vmcnt(18)
	v_mfma_f32_16x16x32_bf16 v[2:5], v[138:141], v[134:137], v[2:5]
	s_waitcnt vmcnt(16)
	v_mfma_f32_16x16x32_bf16 v[6:9], v[158:161], v[142:145], v[6:9]
	s_waitcnt vmcnt(14)
	v_mfma_f32_16x16x32_bf16 v[2:5], v[14:17], v[10:13], v[2:5]
	s_waitcnt vmcnt(12)
	v_mfma_f32_16x16x32_bf16 v[6:9], v[22:25], v[18:21], v[6:9]
	s_waitcnt vmcnt(10)
	v_mfma_f32_16x16x32_bf16 v[2:5], v[30:33], v[26:29], v[2:5]
	s_waitcnt vmcnt(8)
	v_mfma_f32_16x16x32_bf16 v[6:9], v[38:41], v[34:37], v[6:9]
	s_waitcnt vmcnt(6)
	v_mfma_f32_16x16x32_bf16 v[2:5], v[46:49], v[42:45], v[2:5]
	s_waitcnt vmcnt(4)
	v_mfma_f32_16x16x32_bf16 v[10:13], v[54:57], v[50:53], v[6:9]
	s_waitcnt vmcnt(2)
	v_mfma_f32_16x16x32_bf16 v[6:9], v[62:65], v[58:61], v[2:5]
	s_waitcnt vmcnt(0)
	v_mfma_f32_16x16x32_bf16 v[2:5], v[82:85], v[66:69], v[10:13]
	s_nop 3
	global_load_dwordx4 v[10:13], v[74:75], off offset:3584
	global_load_dwordx4 v[14:17], v[70:71], off offset:3584
	global_load_dwordx4 v[18:21], v[74:75], off offset:3648
	global_load_dwordx4 v[22:25], v[70:71], off offset:3648
	global_load_dwordx4 v[26:29], v[74:75], off offset:3712
	global_load_dwordx4 v[30:33], v[70:71], off offset:3712
	global_load_dwordx4 v[34:37], v[74:75], off offset:3776
	global_load_dwordx4 v[38:41], v[70:71], off offset:3776
	global_load_dwordx4 v[42:45], v[74:75], off offset:3840
	global_load_dwordx4 v[46:49], v[70:71], off offset:3840
	global_load_dwordx4 v[50:53], v[74:75], off offset:3904
	global_load_dwordx4 v[54:57], v[70:71], off offset:3904
	global_load_dwordx4 v[58:61], v[74:75], off offset:3968
	global_load_dwordx4 v[62:65], v[70:71], off offset:3968
	global_load_dwordx4 v[66:69], v[74:75], off offset:4032
	s_nop 0
	global_load_dwordx4 v[70:73], v[70:71], off offset:4032
	s_waitcnt vmcnt(14)
	v_mfma_f32_16x16x32_bf16 v[6:9], v[14:17], v[10:13], v[6:9]
	s_waitcnt vmcnt(12)
	v_mfma_f32_16x16x32_bf16 v[2:5], v[22:25], v[18:21], v[2:5]
	s_waitcnt vmcnt(10)
	v_mfma_f32_16x16x32_bf16 v[6:9], v[30:33], v[26:29], v[6:9]
	s_waitcnt vmcnt(8)
	v_mfma_f32_16x16x32_bf16 v[2:5], v[38:41], v[34:37], v[2:5]
	s_waitcnt vmcnt(6)
	v_mfma_f32_16x16x32_bf16 v[6:9], v[46:49], v[42:45], v[6:9]
	s_waitcnt vmcnt(4)
	v_mfma_f32_16x16x32_bf16 v[2:5], v[54:57], v[50:53], v[2:5]
	s_waitcnt vmcnt(2)
	v_mfma_f32_16x16x32_bf16 v[6:9], v[62:65], v[58:61], v[6:9]
	s_waitcnt vmcnt(0)
	v_mfma_f32_16x16x32_bf16 v[2:5], v[70:73], v[66:69], v[2:5]
	s_nop 7
	v_pk_add_f32 v[6:7], v[6:7], v[2:3]
	v_add_u32_e32 v2, v80, v81
	v_ashrrev_i32_e32 v3, 31, v2
	v_lshl_add_u64 v[2:3], v[2:3], 0, v[0:1]
	v_lshlrev_b64 v[10:11], 2, v[2:3]
	v_lshl_add_u64 v[2:3], s[10:11], 0, v[10:11]
	v_pk_add_f32 v[8:9], v[8:9], v[4:5]
	global_load_dwordx4 v[2:5], v[2:3], off
	v_add_u32_e32 v81, s12, v81
	s_waitcnt vmcnt(0)
	v_pk_add_f32 v[4:5], v[8:9], v[4:5]
	v_pk_add_f32 v[2:3], v[6:7], v[2:3]
	v_lshl_add_u64 v[6:7], s[58:59], 0, v[10:11]
	global_store_dwordx4 v[6:7], v[2:5], off
	s_andn2_b64 exec, exec, s[8:9]
	s_cbranch_execnz .LBB0_216

; DI unsigned cvt_pk_bf16(float lo, float hi) { const f32x2_t v = {lo, hi}; const bf16v2_t b = __builtin_convertvector(v, bf16v2_t); return __builtin_bit_cast(unsigned, b); }
; DI float bf2f(short b) { return __uint_as_float(((unsigned)(unsigned short)b) << 16); }
; #define SWZ_XOR(v, x) __int_as_float(__builtin_amdgcn_ds_swizzle(__float_as_int(v), 0x1F | ((x) << 10)))
; DI float half_sum(float v) { v += SWZ_XOR(v, 1); v += SWZ_XOR(v, 2); v += SWZ_XOR(v, 4); v += SWZ_XOR(v, 8); v += SWZ_XOR(v, 16); return v; }
; DI float wave_sum(float v) { v = half_sum(v); auto rr = __builtin_amdgcn_permlane32_swap(__float_as_uint(v), __float_as_uint(v), false, false); return __uint_as_float(rr[0]) + __uint_as_float(rr[1]); }
; DI void phase_gate(int wid0, const Params& p, int L, bool dry) {
;     ...
;     for (int t = gw; t < (MREG + 16) * 4; t += nw) {
;         const int row = t >> 2, hd = t & 3;
;         const bf16_t* op = row < MREG ? vb + (size_t)row * 2048 + hd * 512 + lane * 8 : ometa + (size_t)(row - MREG) * 2048 + hd * 512 + lane * 8;
;         bf16_t* zp = zb + (size_t)row * 2048 + hd * 512 + lane * 8;
;         const bf16x8 ov = *(const bf16x8*)op; const bf16x8 zv = *(const bf16x8*)zp;
;         float of[8], ss = 0.f;
; #pragma unroll
;         for (int e = 0; e < 8; ++e) { of[e] = bf2f(ov[e]); ss += of[e] * of[e]; }
;         ss = wave_sum(ss);
;         const float rstd = rsqrtf(ss * (1.f / 512.f) + 1e-6f);
;         const f32x4 g0 = *(const f32x4*)(gn + hd * 512 + lane * 8), g1 = *(const f32x4*)(gn + hd * 512 + lane * 8 + 4);
;         float y[8];
; #pragma unroll
;         for (int e = 0; e < 8; ++e) { const float z = bf2f(zv[e]); y[e] = z * __builtin_amdgcn_rcpf(1.f + __expf(-z)) * of[e] * rstd * (e < 4 ? g0[e] : g1[e - 4]); }
;         u32x4 w; w.x = cvt_pk_bf16(y[0], y[1]); w.y = cvt_pk_bf16(y[2], y[3]); w.z = cvt_pk_bf16(y[4], y[5]); w.w = cvt_pk_bf16(y[6], y[7]);
;         if (!dry) *(u32x4*)zp = w;
;     }
.LBB0_220:
	s_or_b64 exec, exec, s[10:11]
	v_lshl_add_u64 v[10:11], v[10:11], 0, v[0:1]
	v_lshl_add_u64 v[14:15], v[6:7], 0, v[14:15]
	global_load_dwordx4 v[10:13], v[10:11], off
	s_nop 0
	global_load_dwordx4 v[18:21], v[14:15], off
	global_load_dwordx4 v[22:25], v[8:9], off offset:16
	global_load_dwordx4 v[26:29], v[8:9], off
	v_add_u32_e32 v16, s2, v16
	s_mov_b32 s10, 0x2003f
	s_waitcnt vmcnt(3)
	v_and_b32_e32 v31, 0xffff0000, v13
	s_waitcnt vmcnt(2)
	v_lshlrev_b32_e32 v36, 16, v20
	v_mul_f32_e32 v17, 0xbfb8aa3b, v36
	v_exp_f32_e32 v17, v17
	v_and_b32_e32 v37, 0xffff0000, v20
	v_lshlrev_b32_e32 v30, 16, v13
	v_and_b32_e32 v13, 0xffff0000, v12
	v_add_f32_e32 v17, 1.0, v17
	v_rcp_f32_e32 v38, v17
	v_mul_f32_e32 v17, 0xbfb8aa3b, v37
	v_exp_f32_e32 v17, v17
	v_lshlrev_b32_e32 v12, 16, v12
	v_lshlrev_b32_e32 v40, 16, v19
	v_pk_mul_f32 v[34:35], v[12:13], v[12:13]
	v_add_f32_e32 v17, 1.0, v17
	v_rcp_f32_e32 v39, v17
	v_and_b32_e32 v41, 0xffff0000, v19
	v_and_b32_e32 v19, 0xffff0000, v18
	v_lshlrev_b32_e32 v18, 16, v18
	v_pk_mul_f32 v[36:37], v[38:39], v[36:37]
	v_mul_f32_e32 v17, 0xbfb8aa3b, v18
	v_pk_mul_f32 v[12:13], v[36:37], v[12:13]
	v_and_b32_e32 v37, 0xffff0000, v11
	v_lshlrev_b32_e32 v36, 16, v11
	v_mul_f32_e32 v11, 0xbfb8aa3b, v40
	v_exp_f32_e32 v11, v11
	v_exp_f32_e32 v17, v17
	v_pk_mul_f32 v[38:39], v[36:37], v[36:37]
	v_pk_mul_f32 v[32:33], v[30:31], v[30:31]
	v_add_f32_e32 v11, 1.0, v11
	v_rcp_f32_e32 v42, v11
	v_mul_f32_e32 v11, 0xbfb8aa3b, v41
	v_exp_f32_e32 v11, v11
	v_add_f32_e32 v17, 1.0, v17
	v_add_f32_e32 v11, 1.0, v11
	v_rcp_f32_e32 v43, v11
	v_and_b32_e32 v11, 0xffff0000, v10
	v_lshlrev_b32_e32 v10, 16, v10
	v_pk_mul_f32 v[40:41], v[42:43], v[40:41]
	v_rcp_f32_e32 v42, v17
	v_mul_f32_e32 v17, 0xbfb8aa3b, v19
	v_exp_f32_e32 v17, v17
	v_pk_mul_f32 v[36:37], v[40:41], v[36:37]
	v_pk_mul_f32 v[40:41], v[10:11], v[10:11]
	v_add_f32_e32 v17, 1.0, v17
	v_rcp_f32_e32 v43, v17
	v_add_f32_e32 v17, v40, v41
	v_add_f32_e32 v17, v38, v17
	v_add_f32_e32 v17, v39, v17
	v_add_f32_e32 v17, v34, v17
	v_add_f32_e32 v17, v35, v17
	v_add_f32_e32 v17, v32, v17
	v_pk_mul_f32 v[18:19], v[42:43], v[18:19]
	v_add_f32_e32 v17, v33, v17
	v_pk_mul_f32 v[10:11], v[18:19], v[10:11]
	s_nop 1
	v_add_f32_dpp v17, v17, v17 quad_perm:[1,0,3,2] row_mask:0xf bank_mask:0xf
	s_nop 1
	v_add_f32_dpp v17, v17, v17 quad_perm:[2,3,0,1] row_mask:0xf bank_mask:0xf
	s_nop 1
	v_add_f32_dpp v17, v17, v17 row_half_mirror row_mask:0xf bank_mask:0xf
	s_nop 1
	v_add_f32_dpp v17, v17, v17 row_mirror row_mask:0xf bank_mask:0xf
	ds_swizzle_b32 v18, v17 offset:swizzle(SWAP,16)
	s_waitcnt lgkmcnt(0)
	v_add_f32_e32 v17, v17, v18
	v_mov_b32_e32 v18, v17
	s_nop 1
	v_permlane32_swap_b32_e32 v17, v18
	v_add_f32_e32 v17, v17, v18
	v_fmamk_f32 v17, v17, 0x3b000000, v185
	v_cmp_gt_f32_e32 vcc, s25, v17
	v_mul_f32_e32 v18, 0x4b800000, v17
	s_nop 0
	v_cndmask_b32_e32 v17, v17, v18, vcc
	v_rsq_f32_e32 v17, v17
	s_nop 0
	v_mul_f32_e32 v18, 0x45800000, v17
	v_cndmask_b32_e32 v18, v17, v18, vcc
	v_pk_mul_f32 v[12:13], v[12:13], v[18:19] op_sel_hi:[1,0]
	v_pk_mul_f32 v[10:11], v[10:11], v[18:19] op_sel_hi:[1,0]
	s_waitcnt vmcnt(1)
	v_pk_mul_f32 v[12:13], v[22:23], v[12:13]
	v_lshlrev_b32_e32 v22, 16, v21
	v_mul_f32_e32 v17, 0xbfb8aa3b, v22
	v_exp_f32_e32 v17, v17
	v_and_b32_e32 v23, 0xffff0000, v21
	s_waitcnt vmcnt(0)
	v_pk_mul_f32 v[10:11], v[26:27], v[10:11]
	v_pk_mul_f32 v[26:27], v[36:37], v[18:19] op_sel_hi:[1,0]
	v_add_f32_e32 v17, 1.0, v17
	v_rcp_f32_e32 v20, v17
	v_mul_f32_e32 v17, 0xbfb8aa3b, v23
	v_exp_f32_e32 v17, v17
	v_pk_mul_f32 v[26:27], v[28:29], v[26:27]
	v_cmp_lt_i32_e32 vcc, s10, v16
	v_cvt_pk_bf16_f32 v10, v10, v11
	v_add_f32_e32 v17, 1.0, v17
	v_rcp_f32_e32 v21, v17
	v_cvt_pk_bf16_f32 v11, v26, v27
	v_cvt_pk_bf16_f32 v12, v12, v13
	s_or_b64 s[8:9], vcc, s[8:9]
	v_pk_mul_f32 v[20:21], v[20:21], v[22:23]
	s_nop 0
	v_pk_mul_f32 v[20:21], v[20:21], v[30:31]
	s_nop 0
	v_pk_mul_f32 v[18:19], v[20:21], v[18:19] op_sel_hi:[1,0]
	s_nop 0
	v_pk_mul_f32 v[18:19], v[24:25], v[18:19]
	s_nop 0
	v_cvt_pk_bf16_f32 v13, v18, v19
	global_store_dwordx4 v[14:15], v[10:13], off
	s_andn2_b64 exec, exec, s[8:9]
	s_cbranch_execz .LBB0_225
